# P1 table build: loads of groups 1+2 and of groups 3+4 issued together (two exposed round trips instead of four)
# speedup vs baseline: 1.0002x; 1.0002x over previous
.LBB0_121:
	s_ashr_i32 s4, s54, 31
	s_lshr_b32 s4, s4, 25
	s_add_i32 s4, s54, s4
	s_ashr_i32 s44, s4, 7
	s_mul_i32 s45, s44, 0x6000
	s_mul_hi_i32 s4, s44, 0x6000
	s_add_u32 s10, s49, s45
	s_addc_u32 s11, s50, s4
	s_add_u32 s14, s10, 0x2000
	s_addc_u32 s15, s11, 0
	s_add_i32 s4, s44, 2
	s_add_i32 s5, s45, 0xc000
	s_mul_hi_i32 s4, s4, 0x6000
	s_add_u32 s16, s49, s5
	s_addc_u32 s17, s50, s4
	s_add_u32 s18, s16, 0x2000
	s_addc_u32 s19, s17, 0
	s_add_i32 s4, s44, 4
	s_add_i32 s5, s45, 0x18000
	s_mul_hi_i32 s8, s4, 0x6000
	s_add_u32 s4, s49, s5
	s_addc_u32 s5, s50, s8
	s_add_u32 s8, s4, 0x2000
	s_addc_u32 s9, s5, 0
	s_add_i32 s20, s44, 6
	s_add_i32 s21, s45, 0x24000
	s_mul_hi_i32 s22, s20, 0x6000
	s_add_u32 s20, s49, s21
	s_addc_u32 s21, s50, s22
	s_add_u32 s22, s20, 0x2000
	s_addc_u32 s23, s21, 0
	s_add_i32 s30, s44, 8
	s_add_i32 s31, s45, 0x30000
	s_mul_hi_i32 s34, s30, 0x6000
	s_add_u32 s30, s49, s31
	s_addc_u32 s31, s50, s34
	s_add_u32 s34, s30, 0x2000
	s_addc_u32 s35, s31, 0
	s_add_i32 s36, s44, 10
	s_add_i32 s37, s45, 0x3c000
	s_mul_hi_i32 s38, s36, 0x6000
	s_add_u32 s36, s49, s37
	s_addc_u32 s37, s50, s38
	s_add_u32 s38, s36, 0x2000
	s_addc_u32 s39, s37, 0
	s_add_i32 s40, s44, 12
	s_add_i32 s41, s45, 0x48000
	s_mul_hi_i32 s42, s40, 0x6000
	s_add_u32 s40, s49, s41
	s_addc_u32 s41, s50, s42
	v_lshl_add_u64 v[2:3], s[10:11], 0, v[14:15]
	v_lshl_add_u64 v[4:5], s[14:15], 0, v[14:15]
	v_lshl_add_u64 v[6:7], s[16:17], 0, v[14:15]
	v_lshl_add_u64 v[38:39], s[18:19], 0, v[14:15]
	v_lshl_add_u64 v[8:9], s[4:5], 0, v[14:15]
	flat_load_dword v71, v[16:17] sc1
	flat_load_dword v72, v[18:19] sc1
	flat_load_dword v73, v[2:3] sc1
	flat_load_dword v74, v[4:5] sc1
	flat_load_dword v75, v[6:7] sc1
	flat_load_dword v76, v[38:39] sc1
	flat_load_dword v77, v[8:9] sc1
	s_add_u32 s42, s40, 0x2000
	s_addc_u32 s43, s41, 0
	s_add_i32 s44, s44, 14
	s_add_i32 s45, s45, 0x54000
	s_mul_hi_i32 s46, s44, 0x6000
	s_add_u32 s44, s49, s45
	v_lshl_add_u64 v[60:61], s[8:9], 0, v[14:15]
	s_addc_u32 s45, s50, s46
	v_lshl_add_u64 v[58:59], s[20:21], 0, v[14:15]
	v_lshl_add_u64 v[56:57], s[22:23], 0, v[14:15]
	v_lshl_add_u64 v[54:55], s[30:31], 0, v[14:15]
	v_lshl_add_u64 v[52:53], s[34:35], 0, v[14:15]
	v_lshl_add_u64 v[50:51], s[36:37], 0, v[14:15]
	v_lshl_add_u64 v[48:49], s[38:39], 0, v[14:15]
	v_lshl_add_u64 v[46:47], s[40:41], 0, v[14:15]
	flat_load_dword v78, v[60:61] sc1
	flat_load_dword v79, v[58:59] sc1
	flat_load_dword v80, v[56:57] sc1
	flat_load_dword v81, v[54:55] sc1
	flat_load_dword v82, v[52:53] sc1
	flat_load_dword v83, v[50:51] sc1
	flat_load_dword v84, v[48:49] sc1
	flat_load_dword v85, v[46:47] sc1
	v_lshl_add_u64 v[44:45], s[42:43], 0, v[14:15]
	s_add_u32 s46, s44, 0x2000
	v_lshl_add_u64 v[42:43], s[44:45], 0, v[14:15]
	flat_load_dword v86, v[44:45] sc1
	flat_load_dword v87, v[42:43] sc1
	s_addc_u32 s47, s45, 0
	v_lshl_add_u64 v[40:41], s[46:47], 0, v[14:15]
	flat_load_dword v88, v[40:41] sc1
	flat_load_dword v89, v[20:21] sc1
	v_lshl_add_u64 v[90:91], s[34:35], 0, v[36:37]
	v_lshl_add_u64 v[92:93], s[36:37], 0, v[36:37]
	v_lshl_add_u64 v[94:95], s[38:39], 0, v[36:37]
	v_lshl_add_u64 v[96:97], s[40:41], 0, v[36:37]
	v_lshl_add_u64 v[98:99], s[42:43], 0, v[36:37]
	v_lshl_add_u64 v[100:101], s[44:45], 0, v[36:37]
	v_lshl_add_u64 v[102:103], s[46:47], 0, v[36:37]
	flat_load_dword v160, v[16:17] offset:2048 sc1
	flat_load_dword v104, v[22:23] sc1
	flat_load_dword v105, v[2:3] offset:2048 sc1
	flat_load_dword v106, v[4:5] offset:2048 sc1
	flat_load_dword v107, v[6:7] offset:2048 sc1
	flat_load_dword v108, v[38:39] offset:2048 sc1
	flat_load_dword v109, v[8:9] offset:2048 sc1
	flat_load_dword v110, v[60:61] offset:2048 sc1
	flat_load_dword v111, v[58:59] offset:2048 sc1
	flat_load_dword v112, v[56:57] offset:2048 sc1
	flat_load_dword v113, v[54:55] offset:2048 sc1
	flat_load_dword v114, v[52:53] offset:2048 sc1
	flat_load_dword v115, v[50:51] offset:2048 sc1
	flat_load_dword v116, v[48:49] offset:2048 sc1
	flat_load_dword v117, v[46:47] offset:2048 sc1
	flat_load_dword v118, v[44:45] offset:2048 sc1
	flat_load_dword v119, v[42:43] offset:2048 sc1
	flat_load_dword v120, v[40:41] offset:2048 sc1
	flat_load_dword v121, v[20:21] offset:2048 sc1
	s_waitcnt vmcnt(0) lgkmcnt(0)
	v_add_f32_e32 v71, v71, v73
	v_add_f32_e32 v72, v72, v74
	v_add_f32_e32 v71, v71, v75
	v_add_f32_e32 v72, v72, v76
	v_add_f32_e32 v71, v71, v77
	v_lshl_add_u64 v[74:75], s[14:15], 0, v[36:37]
	v_lshl_add_u64 v[76:77], s[16:17], 0, v[36:37]
	v_add_f32_e32 v72, v72, v78
	v_add_f32_e32 v71, v71, v79
	v_add_f32_e32 v72, v72, v80
	v_add_f32_e32 v71, v71, v81
	v_add_f32_e32 v72, v72, v82
	v_add_f32_e32 v71, v71, v83
	v_add_f32_e32 v72, v72, v84
	v_add_f32_e32 v71, v71, v85
	v_lshl_add_u64 v[78:79], s[18:19], 0, v[36:37]
	v_lshl_add_u64 v[80:81], s[4:5], 0, v[36:37]
	v_add_f32_e32 v72, v72, v86
	v_add_f32_e32 v71, v71, v87
	ds_write_b32 v68, v71 offset:8192
	v_add_f32_e32 v71, v72, v88
	v_add_f32_e32 v71, 1.0, v71
	v_mul_f32_e32 v71, v71, v89
	ds_write_b32 v68, v71
	v_lshl_add_u64 v[72:73], s[10:11], 0, v[36:37]
	v_lshl_add_u64 v[82:83], s[8:9], 0, v[36:37]
	v_lshl_add_u64 v[84:85], s[20:21], 0, v[36:37]
	v_lshl_add_u64 v[86:87], s[22:23], 0, v[36:37]
	v_lshl_add_u64 v[88:89], s[30:31], 0, v[36:37]
	s_waitcnt vmcnt(0) lgkmcnt(0)
	v_add_f32_e32 v71, v160, v105
	v_add_f32_e32 v104, v104, v106
	v_add_f32_e32 v71, v71, v107
	v_add_f32_e32 v104, v104, v108
	v_add_f32_e32 v71, v71, v109
	v_add_f32_e32 v104, v104, v110
	v_add_f32_e32 v71, v71, v111
	v_add_f32_e32 v104, v104, v112
	v_add_f32_e32 v71, v71, v113
	v_add_f32_e32 v104, v104, v114
	v_add_f32_e32 v71, v71, v115
	v_add_f32_e32 v104, v104, v116
	v_add_f32_e32 v71, v71, v117
	v_add_f32_e32 v104, v104, v118
	v_add_f32_e32 v71, v71, v119
	v_add_f32_e32 v104, v104, v120
	v_add_f32_e32 v104, 1.0, v104
	ds_write_b32 v68, v71 offset:10240
	v_mul_f32_e32 v71, v104, v121
	ds_write_b32 v68, v71 offset:2048
	flat_load_dword v71, v[72:73] sc1
	s_nop 0
	flat_load_dword v72, v[74:75] sc1
	flat_load_dword v73, v[24:25] sc1
	flat_load_dword v104, v[26:27] sc1
	flat_load_dword v105, v[76:77] sc1
	flat_load_dword v106, v[78:79] sc1
	flat_load_dword v107, v[80:81] sc1
	flat_load_dword v108, v[82:83] sc1
	flat_load_dword v109, v[84:85] sc1
	flat_load_dword v110, v[86:87] sc1
	flat_load_dword v111, v[88:89] sc1
	flat_load_dword v112, v[90:91] sc1
	flat_load_dword v113, v[92:93] sc1
	flat_load_dword v114, v[94:95] sc1
	flat_load_dword v115, v[96:97] sc1
	flat_load_dword v116, v[98:99] sc1
	flat_load_dword v74, v[100:101] sc1
	flat_load_dword v75, v[102:103] sc1
	flat_load_dword v76, v[28:29] sc1
	s_mov_b64 s[56:57], exec
	s_and_b64 exec, exec, s[6:7]
	v_add_co_u32_e32 v2, vcc, 0x1000, v2
	s_nop 1
	v_addc_co_u32_e32 v3, vcc, 0, v3, vcc
	v_add_co_u32_e32 v4, vcc, 0x1000, v4
	s_nop 1
	v_addc_co_u32_e32 v5, vcc, 0, v5, vcc
	v_add_co_u32_e32 v6, vcc, 0x1000, v6
	s_nop 1
	v_addc_co_u32_e32 v7, vcc, 0, v7, vcc
	v_add_co_u32_e32 v38, vcc, 0x1000, v38
	s_nop 1
	v_addc_co_u32_e32 v39, vcc, 0, v39, vcc
	v_add_co_u32_e32 v8, vcc, 0x1000, v8
	s_nop 1
	v_addc_co_u32_e32 v9, vcc, 0, v9, vcc
	flat_load_dword v161, v[30:31] sc1
	flat_load_dword v162, v[32:33] sc1
	flat_load_dword v163, v[2:3] offset:2048 sc1
	flat_load_dword v164, v[4:5] offset:2048 sc1
	flat_load_dword v165, v[6:7] offset:2048 sc1
	flat_load_dword v166, v[38:39] offset:2048 sc1
	flat_load_dword v167, v[8:9] offset:2048 sc1
	v_add_co_u32_e32 v2, vcc, 0x1000, v60
	s_nop 1
	v_addc_co_u32_e32 v3, vcc, 0, v61, vcc
	v_add_co_u32_e32 v4, vcc, 0x1000, v58
	s_nop 1
	v_addc_co_u32_e32 v5, vcc, 0, v59, vcc
	v_add_co_u32_e32 v6, vcc, 0x1000, v56
	s_nop 1
	v_addc_co_u32_e32 v7, vcc, 0, v57, vcc
	v_add_co_u32_e32 v8, vcc, 0x1000, v54
	s_nop 1
	v_addc_co_u32_e32 v9, vcc, 0, v55, vcc
	v_add_co_u32_e32 v38, vcc, 0x1000, v52
	s_nop 1
	v_addc_co_u32_e32 v39, vcc, 0, v53, vcc
	v_add_co_u32_e32 v50, vcc, 0x1000, v50
	s_nop 1
	v_addc_co_u32_e32 v51, vcc, 0, v51, vcc
	v_add_co_u32_e32 v48, vcc, 0x1000, v48
	s_nop 1
	v_addc_co_u32_e32 v49, vcc, 0, v49, vcc
	v_add_co_u32_e32 v46, vcc, 0x1000, v46
	s_nop 1
	v_addc_co_u32_e32 v47, vcc, 0, v47, vcc
	flat_load_dword v52, v[2:3] offset:2048 sc1
	flat_load_dword v53, v[4:5] offset:2048 sc1
	flat_load_dword v54, v[6:7] offset:2048 sc1
	flat_load_dword v55, v[8:9] offset:2048 sc1
	flat_load_dword v56, v[38:39] offset:2048 sc1
	flat_load_dword v57, v[50:51] offset:2048 sc1
	flat_load_dword v58, v[48:49] offset:2048 sc1
	flat_load_dword v59, v[46:47] offset:2048 sc1
	v_add_co_u32_e32 v2, vcc, 0x1000, v44
	s_nop 1
	v_addc_co_u32_e32 v3, vcc, 0, v45, vcc
	v_add_co_u32_e32 v4, vcc, 0x1000, v42
	s_nop 1
	v_addc_co_u32_e32 v5, vcc, 0, v43, vcc
	v_add_co_u32_e32 v6, vcc, 0x1000, v40
	s_nop 1
	v_addc_co_u32_e32 v7, vcc, 0, v41, vcc
	flat_load_dword v8, v[2:3] offset:2048 sc1
	flat_load_dword v9, v[4:5] offset:2048 sc1
	flat_load_dword v38, v[6:7] offset:2048 sc1
	flat_load_dword v39, v[34:35] sc1
	s_mov_b64 exec, s[56:57]
	s_waitcnt vmcnt(0) lgkmcnt(0)
	v_add_f32_e32 v71, v73, v71
	v_add_f32_e32 v72, v104, v72
	v_add_f32_e32 v71, v71, v105
	v_add_f32_e32 v72, v72, v106
	v_add_f32_e32 v71, v71, v107
	v_add_f32_e32 v72, v72, v108
	v_add_f32_e32 v71, v71, v109
	v_add_f32_e32 v72, v72, v110
	v_add_f32_e32 v71, v71, v111
	v_add_f32_e32 v72, v72, v112
	v_add_f32_e32 v71, v71, v113
	v_add_f32_e32 v72, v72, v114
	v_add_f32_e32 v71, v71, v115
	v_add_f32_e32 v72, v72, v116
	v_add_f32_e32 v71, v71, v74
	v_add_f32_e32 v72, v72, v75
	v_add_f32_e32 v72, 1.0, v72
	v_mul_f32_e32 v72, v72, v76
	ds_write_b32 v68, v72 offset:4096
	ds_write_b32 v68, v71 offset:12288
	s_and_saveexec_b64 s[4:5], s[6:7]
	s_cbranch_execz .LBB0_123
	s_waitcnt vmcnt(0) lgkmcnt(0)
	v_add_f32_e32 v2, v161, v163
	v_add_f32_e32 v3, v162, v164
	v_add_f32_e32 v2, v2, v165
	v_add_f32_e32 v3, v3, v166
	v_add_f32_e32 v2, v2, v167
	v_add_f32_e32 v3, v3, v52
	v_add_f32_e32 v2, v2, v53
	v_add_f32_e32 v3, v3, v54
	v_add_f32_e32 v2, v2, v55
	v_add_f32_e32 v3, v3, v56
	v_add_f32_e32 v2, v2, v57
	v_add_f32_e32 v3, v3, v58
	v_add_f32_e32 v2, v2, v59
	v_add_f32_e32 v3, v3, v8
	v_add_f32_e32 v2, v2, v9
	v_add_f32_e32 v3, v3, v38
	v_add_f32_e32 v3, 1.0, v3
	v_mul_f32_e32 v3, v3, v39
	ds_write2st64_b32 v68, v3, v2 offset0:24 offset1:56
